# first grid-barrier census: 16 device-scope counter loads issued back to back with one wait (was 16 serial round trips); on stacked v12
# speedup vs baseline: 1.0013x; 1.0013x over previous
; __device__ __forceinline__ unsigned xb_ld(unsigned* p)              { return __hip_atomic_load(p, __ATOMIC_RELAXED, __HIP_MEMORY_SCOPE_AGENT); }
; __device__ __forceinline__ void xcd_barrier_complete(unsigned* bar, unsigned x, unsigned& nloc, unsigned& nx) {
;     const unsigned G = gridDim.x * gridDim.y * gridDim.z;
;     unsigned sum, cnt, mine, sp = 0u;
;     for (;;) {
;         sum = 0u; cnt = 0u; mine = 0u;
; #pragma unroll
;         for (unsigned j = 0; j < 16; ++j) { const unsigned c = xb_ld(&bar[XB_XCNT(j)]); sum += c; cnt += (c > 0u) ? 1u : 0u; mine = (j == x) ? c : mine; }
;         if (sum == G) break;
;         __builtin_amdgcn_s_sleep(1);
;         if ((++sp & 255u) == 0u) { if (xb_ld(&bar[XB_TMO])) break; if (sp > XB_SPIN_CAP) { atomicAdd(&bar[XB_TMO], 1u); break; } }
;     }
;     nloc = mine > 0u ? mine : 1u; nx = cnt > 0u ? cnt : 1u;
; }
.LBB0_903:
	v_readlane_b32 s26, v252, 1
	v_readlane_b32 s27, v252, 2
	s_mov_b64 s[28:29], -1
	s_nop 3
	global_load_dword v0, v177, s[26:27] sc1
	v_readlane_b32 s26, v252, 3
	v_readlane_b32 s27, v252, 4
	s_nop 4
	global_load_dword v1, v177, s[26:27] sc1
	v_readlane_b32 s26, v252, 5
	v_readlane_b32 s27, v252, 6
	s_nop 4
	global_load_dword v2, v177, s[26:27] sc1
	v_readlane_b32 s26, v252, 7
	v_readlane_b32 s27, v252, 8
	s_nop 4
	global_load_dword v3, v177, s[26:27] sc1
	v_readlane_b32 s26, v252, 9
	v_readlane_b32 s27, v252, 10
	s_nop 4
	global_load_dword v4, v177, s[26:27] sc1
	v_readlane_b32 s26, v252, 11
	v_readlane_b32 s27, v252, 12
	s_nop 4
	global_load_dword v5, v177, s[26:27] sc1
	v_readlane_b32 s26, v252, 13
	v_readlane_b32 s27, v252, 14
	s_nop 4
	global_load_dword v6, v177, s[26:27] sc1
	v_readlane_b32 s26, v252, 15
	v_readlane_b32 s27, v252, 16
	s_nop 4
	global_load_dword v7, v177, s[26:27] sc1
	v_readlane_b32 s26, v252, 17
	v_readlane_b32 s27, v252, 18
	s_nop 4
	global_load_dword v8, v177, s[26:27] sc1
	v_readlane_b32 s26, v252, 19
	v_readlane_b32 s27, v252, 20
	s_nop 4
	global_load_dword v9, v177, s[26:27] sc1
	v_readlane_b32 s26, v252, 21
	v_readlane_b32 s27, v252, 22
	s_nop 4
	global_load_dword v10, v177, s[26:27] sc1
	v_readlane_b32 s26, v252, 23
	v_readlane_b32 s27, v252, 24
	s_nop 4
	global_load_dword v11, v177, s[26:27] sc1
	v_readlane_b32 s26, v252, 25
	v_readlane_b32 s27, v252, 26
	s_nop 4
	global_load_dword v12, v177, s[26:27] sc1
	v_readlane_b32 s26, v252, 27
	v_readlane_b32 s27, v252, 28
	s_nop 4
	global_load_dword v13, v177, s[26:27] sc1
	v_readlane_b32 s26, v252, 29
	v_readlane_b32 s27, v252, 30
	s_nop 4
	global_load_dword v14, v177, s[26:27] sc1
	v_readlane_b32 s26, v252, 31
	v_readlane_b32 s27, v252, 32
	s_nop 4
	global_load_dword v15, v177, s[26:27] sc1
	s_mov_b64 s[26:27], -1
	s_waitcnt vmcnt(0)
	v_add_u32_e32 v16, v1, v0
	v_add_u32_e32 v16, v16, v2
	v_add_u32_e32 v16, v16, v3
	v_add_u32_e32 v16, v16, v4
	v_add_u32_e32 v16, v16, v5
	v_add_u32_e32 v16, v16, v6
	v_add_u32_e32 v16, v16, v7
	v_add_u32_e32 v16, v16, v8
	v_add_u32_e32 v16, v16, v9
	v_add_u32_e32 v16, v16, v10
	v_add_u32_e32 v16, v16, v11
	v_add_u32_e32 v16, v16, v12
	v_add_u32_e32 v16, v16, v13
	v_add_u32_e32 v16, v16, v14
	v_add_u32_e32 v16, v16, v15
	v_cmp_eq_u32_e32 vcc, s10, v16
	s_cbranch_vccnz .LBB0_902
	s_and_b32 s26, s21, 0xff
	s_cmp_eq_u32 s26, 0
	s_mov_b64 s[26:27], -1
	s_mov_b64 s[30:31], -1
	s_sleep 1
	s_cbranch_scc0 .LBB0_907
	v_readlane_b32 s26, v251, 63
	v_readlane_b32 s27, v252, 0
	s_nop 4
	global_load_dword v16, v177, s[26:27] sc1
	s_waitcnt vmcnt(0)
	v_cmp_eq_u32_e32 vcc, 0, v16
	s_cbranch_vccnz .LBB0_909
	s_mov_b64 s[30:31], 0
	s_mov_b64 s[26:27], -1
